# K-loop L1 segments: 3-way LDS wait split (lgkmcnt 8 before the handoff barrier, 6 before the 5th MFMA, 0 before the 9th)
# speedup vs baseline: 1.0022x; 1.0022x over previous
; #define PG8_STAGE(bufoff, gbase, voff) do { _Pragma("unroll") for (int _i = 0; _i < 2; ++_i) \
;         __builtin_amdgcn_global_load_lds((const unsigned*)((const char*)(gbase) + (voff)[_i]), (LAS unsigned*)(lds + (bufoff) + ldsw + _i * 8192), 16, 0, 0); } while (0)
; #define PG8_LDA(dst, b, h) do { _Pragma("unroll") for (int m = 0; m < 4; ++m) _Pragma("unroll") for (int k = 0; k < 2; ++k) dst[m][k] = *(const LAS bf16x8*)(lds + PG8_SA(b, h) + aoff + m * 2048 + k * 1024); } while (0)
; #define PG8_LDB(dst, b, h) do { _Pragma("unroll") for (int n = 0; n < 2; ++n) _Pragma("unroll") for (int k = 0; k < 2; ++k) dst[n][k] = *(const LAS bf16x8*)(lds + PG8_SB(b, h) + boff + n * 2048 + k * 1024); } while (0)
; #define PG8_MMA(ai, bj, At, Bt) do { __builtin_amdgcn_s_setprio(1); _Pragma("unroll") for (int m = 0; m < 4; ++m) _Pragma("unroll") for (int n = 0; n < 2; ++n) _Pragma("unroll") for (int k = 0; k < 2; ++k) \
;         acc[ai][bj][m][n] = __builtin_amdgcn_mfma_f32_16x16x32_bf16(Bt[n][k], At[m][k], acc[ai][bj][m][n], 0, 0, 0); __builtin_amdgcn_s_setprio(0); } while (0)
; #define PG8_WAIT_V(n) asm volatile("s_waitcnt vmcnt(" #n ")" ::: "memory")
; #define PG8_WAIT_L(n) asm volatile("s_waitcnt lgkmcnt(" #n ")" ::: "memory")
; #define PG8_BAR __builtin_amdgcn_s_barrier()
; template <class Epi>
; __device__ __forceinline__ void gemm_phase(LAS unsigned char* lds, const Gemm g, const StaticOrder& S, const Epi& E) {
;     ...
;         for (; t < tend; t += 2) {
;             const bool last = (t == nt - 2);
;             const char* a1 = cA + (size_t)(t + 1) * kstep;
;             const char* a2 = last ? nA : cA + (size_t)(t + 2) * kstep; const char* b2 = last ? nB : cB + (size_t)(t + 2) * kstep;
;             const char* a3 = a2 + kstep; const char* b3 = b2 + kstep;
;             PG8_LDB(B0, 0, 0); PG8_SCHED; PG8_LDA(At, 0, 0); PG8_STAGE(PG8_SA(1, 1), a1 + hstep, voffA);
;             PG8_WAIT_L(8); PG8_BAR; PG8_WAIT_L(0); PG8_MMA(0, 0, At, B0); PG8_BAR; PG8_SCHED;
;             PG8_LDB(B1, 0, 1); PG8_STAGE(PG8_SB(0, 0), b2, voffB);
;             PG8_BAR; PG8_WAIT_L(0); PG8_MMA(0, 1, At, B1); PG8_BAR;
;             PG8_LDA(At, 0, 1); PG8_STAGE(PG8_SA(0, 0), a2, voffA);
;             PG8_BAR; PG8_WAIT_L(0); PG8_MMA(1, 0, At, B0); PG8_BAR; PG8_SCHED;
;             PG8_STAGE(PG8_SB(0, 1), b2 + hstep, voffB);
;             PG8_WAIT_V(6); PG8_BAR; PG8_MMA(1, 1, At, B1); PG8_BAR;
.LBB0_206:
	s_add_i32 s78, 0, 0x10000
	ds_read_b128 v[132:135], v234
	ds_read_b128 v[140:143], v234 offset:2048
	ds_read_b128 v[148:151], v200
	ds_read_b128 v[156:159], v200 offset:2048
	s_add_i32 s76, s2, 1
	s_mov_b32 s47, s2
	s_add_i32 s2, s2, 2
	s_ashr_i32 s77, s76, 31
	s_cmp_eq_u32 s67, s47
	s_cselect_b32 s75, s43, s46
	s_cselect_b32 s74, s42, vcc_hi
	s_cselect_b32 s93, s63, vcc_lo
	s_cselect_b32 s92, s62, s3
	s_lshl_b64 s[76:77], s[76:77], 7
	s_add_u32 s76, s5, s76
	s_addc_u32 s77, s31, s77
	s_add_i32 m0, s11, 0xc000
	ds_read_b128 v[164:167], v200 offset:4096
	ds_read_b128 v[190:193], v200 offset:6144
	ds_read_b128 v[136:139], v234 offset:1024
	ds_read_b128 v[144:147], v234 offset:3072
	ds_read_b128 v[152:155], v200 offset:1024
	ds_read_b128 v[160:163], v200 offset:3072
	ds_read_b128 v[186:189], v200 offset:5120
	ds_read_b128 v[202:205], v200 offset:7168
	global_load_lds_dwordx4 v168, s[76:77]
	s_add_i32 m0, s11, 0xe000
	s_nop 0
	global_load_lds_dwordx4 v172, s[76:77]
	s_waitcnt lgkmcnt(8)
	s_barrier
	v_mfma_f32_16x16x32_bf16 v[128:131], v[132:135], v[148:151], v[128:131]
	v_mfma_f32_16x16x32_bf16 v[124:127], v[140:143], v[148:151], v[124:127]
	v_mfma_f32_16x16x32_bf16 v[112:115], v[132:135], v[156:159], v[112:115]
	v_mfma_f32_16x16x32_bf16 v[108:111], v[140:143], v[156:159], v[108:111]
	s_waitcnt lgkmcnt(6)
	v_mfma_f32_16x16x32_bf16 v[96:99], v[132:135], v[164:167], v[96:99]
	v_mfma_f32_16x16x32_bf16 v[92:95], v[140:143], v[164:167], v[92:95]
	v_mfma_f32_16x16x32_bf16 v[80:83], v[132:135], v[190:193], v[80:83]
	v_mfma_f32_16x16x32_bf16 v[76:79], v[140:143], v[190:193], v[76:79]
	s_waitcnt lgkmcnt(0)
	v_mfma_f32_16x16x32_bf16 v[128:131], v[136:139], v[152:155], v[128:131]
	v_mfma_f32_16x16x32_bf16 v[124:127], v[144:147], v[152:155], v[124:127]
	v_mfma_f32_16x16x32_bf16 v[112:115], v[136:139], v[160:163], v[112:115]
	v_mfma_f32_16x16x32_bf16 v[108:111], v[144:147], v[160:163], v[108:111]
	v_mfma_f32_16x16x32_bf16 v[96:99], v[136:139], v[186:189], v[96:99]
	v_mfma_f32_16x16x32_bf16 v[92:95], v[144:147], v[186:189], v[92:95]
	v_mfma_f32_16x16x32_bf16 v[80:83], v[136:139], v[202:205], v[80:83]
	v_mfma_f32_16x16x32_bf16 v[76:79], v[144:147], v[202:205], v[76:79]
	s_barrier
	s_add_i32 s47, 0, 0x14000
	s_add_i32 s76, s78, s6
	s_mov_b32 m0, s76
	ds_read_b128 v[206:209], v235
	ds_read_b128 v[226:229], v235 offset:2048
	ds_read_b128 v[222:225], v235 offset:1024
	ds_read_b128 v[230:233], v235 offset:3072
	global_load_lds_dwordx4 v170, s[92:93]
	s_add_i32 m0, s76, 0x2000
	s_nop 0
	global_load_lds_dwordx4 v174, s[92:93]
	s_waitcnt lgkmcnt(2)
	s_barrier
	v_mfma_f32_16x16x32_bf16 v[120:123], v[206:209], v[148:151], v[120:123]
	v_mfma_f32_16x16x32_bf16 v[116:119], v[226:229], v[148:151], v[116:119]
	v_mfma_f32_16x16x32_bf16 v[104:107], v[206:209], v[156:159], v[104:107]
	v_mfma_f32_16x16x32_bf16 v[100:103], v[226:229], v[156:159], v[100:103]
	v_mfma_f32_16x16x32_bf16 v[88:91], v[206:209], v[164:167], v[88:91]
	v_mfma_f32_16x16x32_bf16 v[84:87], v[226:229], v[164:167], v[84:87]
	v_mfma_f32_16x16x32_bf16 v[72:75], v[206:209], v[190:193], v[72:75]
	v_mfma_f32_16x16x32_bf16 v[68:71], v[226:229], v[190:193], v[68:71]
	s_waitcnt lgkmcnt(0)
	v_mfma_f32_16x16x32_bf16 v[120:123], v[222:225], v[152:155], v[120:123]
	v_mfma_f32_16x16x32_bf16 v[116:119], v[230:233], v[152:155], v[116:119]
	v_mfma_f32_16x16x32_bf16 v[104:107], v[222:225], v[160:163], v[104:107]
	v_mfma_f32_16x16x32_bf16 v[100:103], v[230:233], v[160:163], v[100:103]
	v_mfma_f32_16x16x32_bf16 v[88:91], v[222:225], v[186:189], v[88:91]
	v_mfma_f32_16x16x32_bf16 v[84:87], v[230:233], v[186:189], v[84:87]
	v_mfma_f32_16x16x32_bf16 v[72:75], v[222:225], v[202:205], v[72:75]
	v_mfma_f32_16x16x32_bf16 v[68:71], v[230:233], v[202:205], v[68:71]
	s_mov_b32 m0, s11
	s_barrier
	ds_read_b128 v[148:151], v200 offset:16384
	ds_read_b128 v[156:159], v200 offset:18432
	ds_read_b128 v[164:167], v200 offset:20480
	ds_read_b128 v[190:193], v200 offset:22528
	ds_read_b128 v[152:155], v200 offset:17408
	ds_read_b128 v[160:163], v200 offset:19456
	ds_read_b128 v[186:189], v200 offset:21504
	ds_read_b128 v[202:205], v200 offset:23552
	global_load_lds_dwordx4 v168, s[74:75]
	s_mov_b32 m0, s70
	s_nop 0
	global_load_lds_dwordx4 v172, s[74:75]
	s_waitcnt lgkmcnt(4)
	s_barrier
	v_mfma_f32_16x16x32_bf16 v[64:67], v[132:135], v[148:151], v[64:67]
	v_mfma_f32_16x16x32_bf16 v[60:63], v[140:143], v[148:151], v[60:63]
	v_mfma_f32_16x16x32_bf16 v[48:51], v[132:135], v[156:159], v[48:51]
	v_mfma_f32_16x16x32_bf16 v[44:47], v[140:143], v[156:159], v[44:47]
	v_mfma_f32_16x16x32_bf16 v[32:35], v[132:135], v[164:167], v[32:35]
	v_mfma_f32_16x16x32_bf16 v[28:31], v[140:143], v[164:167], v[28:31]
	v_mfma_f32_16x16x32_bf16 v[16:19], v[132:135], v[190:193], v[16:19]
	v_mfma_f32_16x16x32_bf16 v[12:15], v[140:143], v[190:193], v[12:15]
	s_waitcnt lgkmcnt(0)
	v_mfma_f32_16x16x32_bf16 v[64:67], v[136:139], v[152:155], v[64:67]
	v_mfma_f32_16x16x32_bf16 v[60:63], v[144:147], v[152:155], v[60:63]
	v_mfma_f32_16x16x32_bf16 v[48:51], v[136:139], v[160:163], v[48:51]
	v_mfma_f32_16x16x32_bf16 v[44:47], v[144:147], v[160:163], v[44:47]
	v_mfma_f32_16x16x32_bf16 v[32:35], v[136:139], v[186:189], v[32:35]
	v_mfma_f32_16x16x32_bf16 v[28:31], v[144:147], v[186:189], v[28:31]
	v_mfma_f32_16x16x32_bf16 v[16:19], v[136:139], v[202:205], v[16:19]
	v_mfma_f32_16x16x32_bf16 v[12:15], v[144:147], v[202:205], v[12:15]
	s_barrier
	s_add_u32 s76, s92, s13
	s_addc_u32 s77, s93, 0
	s_add_i32 s47, s47, s6
	s_mov_b32 m0, s47
	s_nop 0
	global_load_lds_dwordx4 v170, s[76:77]
	s_add_i32 m0, s47, 0x2000
	s_nop 0
	global_load_lds_dwordx4 v174, s[76:77]
	s_waitcnt vmcnt(6)
	s_barrier
; #define PG8_STAGE(bufoff, gbase, voff) do { _Pragma("unroll") for (int _i = 0; _i < 2; ++_i) \
;         __builtin_amdgcn_global_load_lds((const unsigned*)((const char*)(gbase) + (voff)[_i]), (LAS unsigned*)(lds + (bufoff) + ldsw + _i * 8192), 16, 0, 0); } while (0)
; #define PG8_LDA(dst, b, h) do { _Pragma("unroll") for (int m = 0; m < 4; ++m) _Pragma("unroll") for (int k = 0; k < 2; ++k) dst[m][k] = *(const LAS bf16x8*)(lds + PG8_SA(b, h) + aoff + m * 2048 + k * 1024); } while (0)
; #define PG8_LDB(dst, b, h) do { _Pragma("unroll") for (int n = 0; n < 2; ++n) _Pragma("unroll") for (int k = 0; k < 2; ++k) dst[n][k] = *(const LAS bf16x8*)(lds + PG8_SB(b, h) + boff + n * 2048 + k * 1024); } while (0)
; #define PG8_MMA(ai, bj, At, Bt) do { __builtin_amdgcn_s_setprio(1); _Pragma("unroll") for (int m = 0; m < 4; ++m) _Pragma("unroll") for (int n = 0; n < 2; ++n) _Pragma("unroll") for (int k = 0; k < 2; ++k) \
;         acc[ai][bj][m][n] = __builtin_amdgcn_mfma_f32_16x16x32_bf16(Bt[n][k], At[m][k], acc[ai][bj][m][n], 0, 0, 0); __builtin_amdgcn_s_setprio(0); } while (0)
; #define PG8_WAIT_V(n) asm volatile("s_waitcnt vmcnt(" #n ")" ::: "memory")
; #define PG8_WAIT_L(n) asm volatile("s_waitcnt lgkmcnt(" #n ")" ::: "memory")
; #define PG8_BAR __builtin_amdgcn_s_barrier()
; #define PG8_SCHED __builtin_amdgcn_sched_barrier(0)
; template <class Epi>
; __device__ __forceinline__ void gemm_phase(LAS unsigned char* lds, const Gemm g, const StaticOrder& S, const Epi& E) {
;     ...
;             PG8_WAIT_V(6); PG8_BAR; PG8_MMA(1, 1, At, B1); PG8_BAR;
;             PG8_LDB(B0, 1, 0); PG8_SCHED; PG8_LDA(At, 1, 0); PG8_STAGE(PG8_SA(0, 1), a2 + hstep, voffA);
;             PG8_WAIT_L(8); PG8_BAR; PG8_WAIT_L(0); PG8_MMA(0, 0, At, B0); PG8_BAR; PG8_SCHED;
;             PG8_LDB(B1, 1, 1); PG8_STAGE(PG8_SB(1, 0), b3, voffB);
;             PG8_BAR; PG8_WAIT_L(0); PG8_MMA(0, 1, At, B1); PG8_BAR;
	v_mfma_f32_16x16x32_bf16 v[56:59], v[206:209], v[148:151], v[56:59]
	v_mfma_f32_16x16x32_bf16 v[52:55], v[226:229], v[148:151], v[52:55]
	v_mfma_f32_16x16x32_bf16 v[40:43], v[206:209], v[156:159], v[40:43]
	v_mfma_f32_16x16x32_bf16 v[36:39], v[226:229], v[156:159], v[36:39]
	v_mfma_f32_16x16x32_bf16 v[24:27], v[206:209], v[164:167], v[24:27]
	v_mfma_f32_16x16x32_bf16 v[20:23], v[226:229], v[164:167], v[20:23]
	v_mfma_f32_16x16x32_bf16 v[8:11], v[206:209], v[190:193], v[8:11]
	v_mfma_f32_16x16x32_bf16 v[4:7], v[226:229], v[190:193], v[4:7]
	v_mfma_f32_16x16x32_bf16 v[56:59], v[222:225], v[152:155], v[56:59]
	v_mfma_f32_16x16x32_bf16 v[52:55], v[230:233], v[152:155], v[52:55]
	v_mfma_f32_16x16x32_bf16 v[40:43], v[222:225], v[160:163], v[40:43]
	v_mfma_f32_16x16x32_bf16 v[36:39], v[230:233], v[160:163], v[36:39]
	v_mfma_f32_16x16x32_bf16 v[24:27], v[222:225], v[186:189], v[24:27]
	v_mfma_f32_16x16x32_bf16 v[20:23], v[230:233], v[186:189], v[20:23]
	v_mfma_f32_16x16x32_bf16 v[8:11], v[222:225], v[202:205], v[8:11]
	v_mfma_f32_16x16x32_bf16 v[4:7], v[230:233], v[202:205], v[4:7]
	s_add_i32 s47, 0, 0x18000
	s_barrier
	ds_read_b128 v[132:135], v236
	ds_read_b128 v[140:143], v236 offset:2048
	ds_read_b128 v[148:151], v200 offset:32768
	ds_read_b128 v[156:159], v200 offset:34816
	s_add_u32 s76, s74, s13
	s_addc_u32 s77, s75, 0
	s_mov_b32 m0, s71
	ds_read_b128 v[164:167], v200 offset:36864
	ds_read_b128 v[190:193], v200 offset:38912
	ds_read_b128 v[136:139], v236 offset:1024
	ds_read_b128 v[144:147], v236 offset:3072
	ds_read_b128 v[152:155], v200 offset:33792
	ds_read_b128 v[160:163], v200 offset:35840
	ds_read_b128 v[186:189], v200 offset:37888
	ds_read_b128 v[202:205], v200 offset:39936
	global_load_lds_dwordx4 v168, s[76:77]
	s_mov_b32 m0, s19
	s_nop 0
	global_load_lds_dwordx4 v172, s[76:77]
	s_waitcnt lgkmcnt(8)
	s_barrier
	v_mfma_f32_16x16x32_bf16 v[128:131], v[132:135], v[148:151], v[128:131]
	v_mfma_f32_16x16x32_bf16 v[124:127], v[140:143], v[148:151], v[124:127]
	v_mfma_f32_16x16x32_bf16 v[112:115], v[132:135], v[156:159], v[112:115]
	v_mfma_f32_16x16x32_bf16 v[108:111], v[140:143], v[156:159], v[108:111]
	s_waitcnt lgkmcnt(6)
	v_mfma_f32_16x16x32_bf16 v[96:99], v[132:135], v[164:167], v[96:99]
	v_mfma_f32_16x16x32_bf16 v[92:95], v[140:143], v[164:167], v[92:95]
	v_mfma_f32_16x16x32_bf16 v[80:83], v[132:135], v[190:193], v[80:83]
	v_mfma_f32_16x16x32_bf16 v[76:79], v[140:143], v[190:193], v[76:79]
	s_waitcnt lgkmcnt(0)
	v_mfma_f32_16x16x32_bf16 v[128:131], v[136:139], v[152:155], v[128:131]
	v_mfma_f32_16x16x32_bf16 v[124:127], v[144:147], v[152:155], v[124:127]
	v_mfma_f32_16x16x32_bf16 v[112:115], v[136:139], v[160:163], v[112:115]
	v_mfma_f32_16x16x32_bf16 v[108:111], v[144:147], v[160:163], v[108:111]
	v_mfma_f32_16x16x32_bf16 v[96:99], v[136:139], v[186:189], v[96:99]
	v_mfma_f32_16x16x32_bf16 v[92:95], v[144:147], v[186:189], v[92:95]
	v_mfma_f32_16x16x32_bf16 v[80:83], v[136:139], v[202:205], v[80:83]
	v_mfma_f32_16x16x32_bf16 v[76:79], v[144:147], v[202:205], v[76:79]
	s_barrier
	s_add_i32 s47, s47, s6
	s_add_u32 s76, s92, 0x80
	s_addc_u32 s77, s93, 0
	s_mov_b32 m0, s47
	ds_read_b128 v[206:209], v237
	ds_read_b128 v[226:229], v237 offset:2048
	ds_read_b128 v[222:225], v237 offset:1024
	ds_read_b128 v[230:233], v237 offset:3072
	global_load_lds_dwordx4 v170, s[76:77]
	s_add_i32 m0, s47, 0x2000
	s_nop 0
	global_load_lds_dwordx4 v174, s[76:77]
	s_waitcnt lgkmcnt(2)
	s_barrier
; #define PG8_STAGE(bufoff, gbase, voff) do { _Pragma("unroll") for (int _i = 0; _i < 2; ++_i) \
;         __builtin_amdgcn_global_load_lds((const unsigned*)((const char*)(gbase) + (voff)[_i]), (LAS unsigned*)(lds + (bufoff) + ldsw + _i * 8192), 16, 0, 0); } while (0)
; #define PG8_LDA(dst, b, h) do { _Pragma("unroll") for (int m = 0; m < 4; ++m) _Pragma("unroll") for (int k = 0; k < 2; ++k) dst[m][k] = *(const LAS bf16x8*)(lds + PG8_SA(b, h) + aoff + m * 2048 + k * 1024); } while (0)
; #define PG8_MMA(ai, bj, At, Bt) do { __builtin_amdgcn_s_setprio(1); _Pragma("unroll") for (int m = 0; m < 4; ++m) _Pragma("unroll") for (int n = 0; n < 2; ++n) _Pragma("unroll") for (int k = 0; k < 2; ++k) \
;         acc[ai][bj][m][n] = __builtin_amdgcn_mfma_f32_16x16x32_bf16(Bt[n][k], At[m][k], acc[ai][bj][m][n], 0, 0, 0); __builtin_amdgcn_s_setprio(0); } while (0)
; #define PG8_WAIT_V(n) asm volatile("s_waitcnt vmcnt(" #n ")" ::: "memory")
; #define PG8_WAIT_L(n) asm volatile("s_waitcnt lgkmcnt(" #n ")" ::: "memory")
; #define PG8_BAR __builtin_amdgcn_s_barrier()
; #define PG8_SCHED __builtin_amdgcn_sched_barrier(0)
; template <class Epi>
; __device__ __forceinline__ void gemm_phase(LAS unsigned char* lds, const Gemm g, const StaticOrder& S, const Epi& E) {
;     ...
;             PG8_BAR; PG8_WAIT_L(0); PG8_MMA(0, 1, At, B1); PG8_BAR;
;             PG8_LDA(At, 1, 1); PG8_STAGE(PG8_SA(1, 0), a3, voffA);
;             PG8_BAR; PG8_WAIT_L(0); PG8_MMA(1, 0, At, B0); PG8_BAR; PG8_SCHED;
;             PG8_STAGE(PG8_SB(1, 1), b3 + hstep, voffB);
;             PG8_WAIT_V(6); PG8_BAR; PG8_MMA(1, 1, At, B1); PG8_BAR;
	v_mfma_f32_16x16x32_bf16 v[120:123], v[206:209], v[148:151], v[120:123]
	v_mfma_f32_16x16x32_bf16 v[116:119], v[226:229], v[148:151], v[116:119]
	v_mfma_f32_16x16x32_bf16 v[104:107], v[206:209], v[156:159], v[104:107]
	v_mfma_f32_16x16x32_bf16 v[100:103], v[226:229], v[156:159], v[100:103]
	v_mfma_f32_16x16x32_bf16 v[88:91], v[206:209], v[164:167], v[88:91]
	v_mfma_f32_16x16x32_bf16 v[84:87], v[226:229], v[164:167], v[84:87]
	v_mfma_f32_16x16x32_bf16 v[72:75], v[206:209], v[190:193], v[72:75]
	v_mfma_f32_16x16x32_bf16 v[68:71], v[226:229], v[190:193], v[68:71]
	s_waitcnt lgkmcnt(0)
	v_mfma_f32_16x16x32_bf16 v[120:123], v[222:225], v[152:155], v[120:123]
	v_mfma_f32_16x16x32_bf16 v[116:119], v[230:233], v[152:155], v[116:119]
	v_mfma_f32_16x16x32_bf16 v[104:107], v[222:225], v[160:163], v[104:107]
	v_mfma_f32_16x16x32_bf16 v[100:103], v[230:233], v[160:163], v[100:103]
	v_mfma_f32_16x16x32_bf16 v[88:91], v[222:225], v[186:189], v[88:91]
	v_mfma_f32_16x16x32_bf16 v[84:87], v[230:233], v[186:189], v[84:87]
	v_mfma_f32_16x16x32_bf16 v[72:75], v[222:225], v[202:205], v[72:75]
	v_mfma_f32_16x16x32_bf16 v[68:71], v[230:233], v[202:205], v[68:71]
	s_mov_b32 m0, s33
	s_add_u32 s76, s74, 0x80
	s_addc_u32 s77, s75, 0
	s_barrier
	ds_read_b128 v[148:151], v200 offset:49152
	ds_read_b128 v[156:159], v200 offset:51200
	ds_read_b128 v[164:167], v200 offset:53248
	ds_read_b128 v[190:193], v200 offset:55296
	ds_read_b128 v[152:155], v200 offset:50176
	ds_read_b128 v[160:163], v200 offset:52224
	ds_read_b128 v[186:189], v200 offset:54272
	ds_read_b128 v[202:205], v200 offset:56320
	global_load_lds_dwordx4 v168, s[76:77]
	s_mov_b32 m0, s66
	s_nop 0
	global_load_lds_dwordx4 v172, s[76:77]
	s_waitcnt lgkmcnt(4)
	s_barrier
	v_mfma_f32_16x16x32_bf16 v[64:67], v[132:135], v[148:151], v[64:67]
	v_mfma_f32_16x16x32_bf16 v[60:63], v[140:143], v[148:151], v[60:63]
	v_mfma_f32_16x16x32_bf16 v[48:51], v[132:135], v[156:159], v[48:51]
	v_mfma_f32_16x16x32_bf16 v[44:47], v[140:143], v[156:159], v[44:47]
	v_mfma_f32_16x16x32_bf16 v[32:35], v[132:135], v[164:167], v[32:35]
	v_mfma_f32_16x16x32_bf16 v[28:31], v[140:143], v[164:167], v[28:31]
	v_mfma_f32_16x16x32_bf16 v[16:19], v[132:135], v[190:193], v[16:19]
	v_mfma_f32_16x16x32_bf16 v[12:15], v[140:143], v[190:193], v[12:15]
	s_waitcnt lgkmcnt(0)
	v_mfma_f32_16x16x32_bf16 v[64:67], v[136:139], v[152:155], v[64:67]
	v_mfma_f32_16x16x32_bf16 v[60:63], v[144:147], v[152:155], v[60:63]
	v_mfma_f32_16x16x32_bf16 v[48:51], v[136:139], v[160:163], v[48:51]
	v_mfma_f32_16x16x32_bf16 v[44:47], v[144:147], v[160:163], v[44:47]
	v_mfma_f32_16x16x32_bf16 v[32:35], v[136:139], v[186:189], v[32:35]
	v_mfma_f32_16x16x32_bf16 v[28:31], v[144:147], v[186:189], v[28:31]
	v_mfma_f32_16x16x32_bf16 v[16:19], v[136:139], v[202:205], v[16:19]
	v_mfma_f32_16x16x32_bf16 v[12:15], v[144:147], v[202:205], v[12:15]
	s_barrier
	s_add_i32 s47, s6, 0x1c000
	s_add_u32 s76, s92, s13
	s_addc_u32 s77, s93, 0
	s_add_u32 s76, s76, 0x80
	s_addc_u32 s77, s77, 0
	s_mov_b32 m0, s47
	s_nop 0
	global_load_lds_dwordx4 v170, s[76:77]
	s_add_i32 m0, s47, 0x2000
	s_nop 0
	global_load_lds_dwordx4 v174, s[76:77]
	s_waitcnt vmcnt(6)
	s_barrier
	v_mfma_f32_16x16x32_bf16 v[56:59], v[206:209], v[148:151], v[56:59]
	v_mfma_f32_16x16x32_bf16 v[52:55], v[226:229], v[148:151], v[52:55]
	v_mfma_f32_16x16x32_bf16 v[40:43], v[206:209], v[156:159], v[40:43]
	v_mfma_f32_16x16x32_bf16 v[36:39], v[226:229], v[156:159], v[36:39]
	v_mfma_f32_16x16x32_bf16 v[24:27], v[206:209], v[164:167], v[24:27]
	v_mfma_f32_16x16x32_bf16 v[20:23], v[226:229], v[164:167], v[20:23]
	v_mfma_f32_16x16x32_bf16 v[8:11], v[206:209], v[190:193], v[8:11]
	v_mfma_f32_16x16x32_bf16 v[4:7], v[226:229], v[190:193], v[4:7]
	v_mfma_f32_16x16x32_bf16 v[56:59], v[222:225], v[152:155], v[56:59]
	v_mfma_f32_16x16x32_bf16 v[52:55], v[230:233], v[152:155], v[52:55]
	v_mfma_f32_16x16x32_bf16 v[40:43], v[222:225], v[160:163], v[40:43]
	v_mfma_f32_16x16x32_bf16 v[36:39], v[230:233], v[160:163], v[36:39]
	v_mfma_f32_16x16x32_bf16 v[24:27], v[222:225], v[186:189], v[24:27]
	v_mfma_f32_16x16x32_bf16 v[20:23], v[230:233], v[186:189], v[20:23]
	v_mfma_f32_16x16x32_bf16 v[8:11], v[222:225], v[202:205], v[8:11]
	v_mfma_f32_16x16x32_bf16 v[4:7], v[230:233], v[202:205], v[4:7]
	s_add_u32 s3, s3, 0x100
	s_addc_u32 vcc_lo, vcc_lo, 0
	s_add_u32 vcc_hi, vcc_hi, 0x100
	s_addc_u32 s46, s46, 0
	s_cmp_lt_i32 s2, s57
	s_barrier
	s_cbranch_scc1 .LBB0_206
	s_movk_i32 s92, 0x90
	s_mov_b32 s93, 0x3f317217
